# final phase hand-written: post_w kept in registers, a whole row (17 requests) in flight and the next row requested while a row is computed; nt hints as before
# speedup vs baseline: 1.0273x; 1.0013x over previous
.LBB0_942:
	s_or_b64 exec, exec, s[2:3]
	s_waitcnt lgkmcnt(0)
	v_add_u32_e32 v0, s64, v196
	s_movk_i32 s0, 0x4000
	v_cmp_gt_i32_e32 vcc, s0, v0
	s_barrier
	v_readfirstlane_b32 s0, v196
	v_readlane_b32 s8, v236, 3
	v_readlane_b32 s9, v236, 4
	v_lshlrev_b32_e32 v136, 4, v197
	v_lshlrev_b32_e32 v137, 3, v197
	v_lshlrev_b32_e32 v138, 2, v197
	v_xor_b32_e32 v130, 32, v197
	v_lshlrev_b32_e32 v130, 2, v130
	v_xor_b32_e32 v131, 16, v197
	v_lshlrev_b32_e32 v131, 2, v131
	v_xor_b32_e32 v132, 8, v197
	v_lshlrev_b32_e32 v132, 2, v132
	v_xor_b32_e32 v133, 4, v197
	v_lshlrev_b32_e32 v133, 2, v133
	v_xor_b32_e32 v134, 2, v197
	v_lshlrev_b32_e32 v134, 2, v134
	v_xor_b32_e32 v135, 1, v197
	v_lshlrev_b32_e32 v135, 2, v135
	v_mov_b32_e32 v154, 0x358637bd
	s_add_u32 s24, s64, s0
	s_mov_b32 s25, s24
	s_add_u32 s2, s60, 0x1000
	s_addc_u32 s3, s61, 0
	global_load_dwordx4 v[96:99], v136, s[60:61] offset:0
	global_load_dwordx4 v[100:103], v136, s[60:61] offset:1024
	global_load_dwordx4 v[104:107], v136, s[60:61] offset:2048
	global_load_dwordx4 v[108:111], v136, s[60:61] offset:3072
	global_load_dwordx4 v[112:115], v136, s[2:3] offset:0
	global_load_dwordx4 v[116:119], v136, s[2:3] offset:1024
	global_load_dwordx4 v[120:123], v136, s[2:3] offset:2048
	global_load_dwordx4 v[124:127], v136, s[2:3] offset:3072
	s_lshl_b32 s1, s24, 13
	s_add_u32 s10, s8, s1
	s_addc_u32 s11, s9, 0
	s_add_u32 s12, s10, 0x1000
	s_addc_u32 s13, s11, 0
	s_lshl_b32 s1, s24, 12
	s_add_u32 s18, s54, s1
	s_addc_u32 s19, s55, 0
	s_lshl_b32 s1, s24, 7
	s_add_u32 s20, s74, s1
	s_addc_u32 s21, s75, 0
	v_mov_b32_e32 v128, 0
	s_mov_b32 exec_hi, 0
	global_load_dword v128, v138, s[20:21]
	s_mov_b64 exec, -1
	global_load_dwordx2 v[64:65], v137, s[18:19] offset:0 nt
	global_load_dwordx2 v[66:67], v137, s[18:19] offset:512 nt
	global_load_dwordx2 v[68:69], v137, s[18:19] offset:1024 nt
	global_load_dwordx2 v[70:71], v137, s[18:19] offset:1536 nt
	global_load_dwordx2 v[72:73], v137, s[18:19] offset:2048 nt
	global_load_dwordx2 v[74:75], v137, s[18:19] offset:2560 nt
	global_load_dwordx2 v[76:77], v137, s[18:19] offset:3072 nt
	global_load_dwordx2 v[78:79], v137, s[18:19] offset:3584 nt
	global_load_dwordx4 v[0:3], v136, s[10:11] offset:0 nt
	global_load_dwordx4 v[4:7], v136, s[10:11] offset:1024 nt
	global_load_dwordx4 v[8:11], v136, s[10:11] offset:2048 nt
	global_load_dwordx4 v[12:15], v136, s[10:11] offset:3072 nt
	global_load_dwordx4 v[16:19], v136, s[12:13] offset:0 nt
	global_load_dwordx4 v[20:23], v136, s[12:13] offset:1024 nt
	global_load_dwordx4 v[24:27], v136, s[12:13] offset:2048 nt
	global_load_dwordx4 v[28:31], v136, s[12:13] offset:3072 nt
	s_add_u32 s24, s24, 0x800
	s_mov_b32 s26, 0
.Lfin_loop:
	s_lshl_b32 s1, s24, 13
	s_add_u32 s10, s8, s1
	s_addc_u32 s11, s9, 0
	s_add_u32 s12, s10, 0x1000
	s_addc_u32 s13, s11, 0
	s_lshl_b32 s1, s24, 12
	s_add_u32 s18, s54, s1
	s_addc_u32 s19, s55, 0
	s_lshl_b32 s1, s24, 7
	s_add_u32 s20, s74, s1
	s_addc_u32 s21, s75, 0
	v_mov_b32_e32 v129, 0
	s_mov_b32 exec_hi, 0
	global_load_dword v129, v138, s[20:21]
	s_mov_b64 exec, -1
	global_load_dwordx2 v[80:81], v137, s[18:19] offset:0 nt
	global_load_dwordx2 v[82:83], v137, s[18:19] offset:512 nt
	global_load_dwordx2 v[84:85], v137, s[18:19] offset:1024 nt
	global_load_dwordx2 v[86:87], v137, s[18:19] offset:1536 nt
	global_load_dwordx2 v[88:89], v137, s[18:19] offset:2048 nt
	global_load_dwordx2 v[90:91], v137, s[18:19] offset:2560 nt
	global_load_dwordx2 v[92:93], v137, s[18:19] offset:3072 nt
	global_load_dwordx2 v[94:95], v137, s[18:19] offset:3584 nt
	global_load_dwordx4 v[32:35], v136, s[10:11] offset:0 nt
	global_load_dwordx4 v[36:39], v136, s[10:11] offset:1024 nt
	global_load_dwordx4 v[40:43], v136, s[10:11] offset:2048 nt
	global_load_dwordx4 v[44:47], v136, s[10:11] offset:3072 nt
	global_load_dwordx4 v[48:51], v136, s[12:13] offset:0 nt
	global_load_dwordx4 v[52:55], v136, s[12:13] offset:1024 nt
	global_load_dwordx4 v[56:59], v136, s[12:13] offset:2048 nt
	global_load_dwordx4 v[60:63], v136, s[12:13] offset:3072 nt
	s_add_u32 s24, s24, 0x800
	s_waitcnt vmcnt(17)
	v_mov_b32_e32 v140, v128
	ds_bpermute_b32 v141, v130, v140
	s_waitcnt lgkmcnt(0)
	v_add_f32_e32 v140, v140, v141
	ds_bpermute_b32 v141, v131, v140
	s_waitcnt lgkmcnt(0)
	v_add_f32_e32 v140, v140, v141
	ds_bpermute_b32 v141, v132, v140
	s_waitcnt lgkmcnt(0)
	v_add_f32_e32 v140, v140, v141
	ds_bpermute_b32 v141, v133, v140
	s_waitcnt lgkmcnt(0)
	v_add_f32_e32 v140, v140, v141
	ds_bpermute_b32 v141, v134, v140
	s_waitcnt lgkmcnt(0)
	v_add_f32_e32 v140, v140, v141
	ds_bpermute_b32 v141, v135, v140
	s_waitcnt lgkmcnt(0)
	v_add_f32_e32 v140, v140, v141
	v_fmamk_f32 v140, v140, 0x3a000000, v154
	s_mov_b32 s1, 0x800000
	v_mul_f32_e32 v142, 0x4b800000, v140
	v_cmp_gt_f32_e64 s[2:3], s1, v140
	s_nop 1
	v_cndmask_b32_e64 v140, v140, v142, s[2:3]
	v_rsq_f32_e32 v140, v140
	s_nop 0
	v_mul_f32_e32 v142, 0x45800000, v140
	v_cndmask_b32_e64 v144, v140, v142, s[2:3]
	s_lshl_b32 s1, s25, 13
	s_add_u32 s14, s62, s1
	s_addc_u32 s15, s63, 0
	s_add_u32 s16, s14, 0x1000
	s_addc_u32 s17, s15, 0
	s_add_u32 s25, s25, 0x800
	v_lshlrev_b32_e32 v146, 16, v64
	v_and_b32_e32 v147, 0xffff0000, v64
	v_lshlrev_b32_e32 v148, 16, v65
	v_and_b32_e32 v149, 0xffff0000, v65
	v_pk_mul_f32 v[146:147], v[144:145], v[146:147] op_sel_hi:[0,1]
	v_pk_mul_f32 v[148:149], v[144:145], v[148:149] op_sel_hi:[0,1]
	v_pk_fma_f32 v[150:151], v[96:97], v[146:147], v[0:1]
	v_pk_fma_f32 v[152:153], v[98:99], v[148:149], v[2:3]
	global_store_dwordx4 v136, v[150:153], s[14:15] offset:0 nt
	v_lshlrev_b32_e32 v146, 16, v66
	v_and_b32_e32 v147, 0xffff0000, v66
	v_lshlrev_b32_e32 v148, 16, v67
	v_and_b32_e32 v149, 0xffff0000, v67
	v_pk_mul_f32 v[146:147], v[144:145], v[146:147] op_sel_hi:[0,1]
	v_pk_mul_f32 v[148:149], v[144:145], v[148:149] op_sel_hi:[0,1]
	v_pk_fma_f32 v[150:151], v[100:101], v[146:147], v[4:5]
	v_pk_fma_f32 v[152:153], v[102:103], v[148:149], v[6:7]
	global_store_dwordx4 v136, v[150:153], s[14:15] offset:1024 nt
	v_lshlrev_b32_e32 v146, 16, v68
	v_and_b32_e32 v147, 0xffff0000, v68
	v_lshlrev_b32_e32 v148, 16, v69
	v_and_b32_e32 v149, 0xffff0000, v69
	v_pk_mul_f32 v[146:147], v[144:145], v[146:147] op_sel_hi:[0,1]
	v_pk_mul_f32 v[148:149], v[144:145], v[148:149] op_sel_hi:[0,1]
	v_pk_fma_f32 v[150:151], v[104:105], v[146:147], v[8:9]
	v_pk_fma_f32 v[152:153], v[106:107], v[148:149], v[10:11]
	global_store_dwordx4 v136, v[150:153], s[14:15] offset:2048 nt
	v_lshlrev_b32_e32 v146, 16, v70
	v_and_b32_e32 v147, 0xffff0000, v70
	v_lshlrev_b32_e32 v148, 16, v71
	v_and_b32_e32 v149, 0xffff0000, v71
	v_pk_mul_f32 v[146:147], v[144:145], v[146:147] op_sel_hi:[0,1]
	v_pk_mul_f32 v[148:149], v[144:145], v[148:149] op_sel_hi:[0,1]
	v_pk_fma_f32 v[150:151], v[108:109], v[146:147], v[12:13]
	v_pk_fma_f32 v[152:153], v[110:111], v[148:149], v[14:15]
	global_store_dwordx4 v136, v[150:153], s[14:15] offset:3072 nt
	v_lshlrev_b32_e32 v146, 16, v72
	v_and_b32_e32 v147, 0xffff0000, v72
	v_lshlrev_b32_e32 v148, 16, v73
	v_and_b32_e32 v149, 0xffff0000, v73
	v_pk_mul_f32 v[146:147], v[144:145], v[146:147] op_sel_hi:[0,1]
	v_pk_mul_f32 v[148:149], v[144:145], v[148:149] op_sel_hi:[0,1]
	v_pk_fma_f32 v[150:151], v[112:113], v[146:147], v[16:17]
	v_pk_fma_f32 v[152:153], v[114:115], v[148:149], v[18:19]
	global_store_dwordx4 v136, v[150:153], s[16:17] offset:0 nt
	v_lshlrev_b32_e32 v146, 16, v74
	v_and_b32_e32 v147, 0xffff0000, v74
	v_lshlrev_b32_e32 v148, 16, v75
	v_and_b32_e32 v149, 0xffff0000, v75
	v_pk_mul_f32 v[146:147], v[144:145], v[146:147] op_sel_hi:[0,1]
	v_pk_mul_f32 v[148:149], v[144:145], v[148:149] op_sel_hi:[0,1]
	v_pk_fma_f32 v[150:151], v[116:117], v[146:147], v[20:21]
	v_pk_fma_f32 v[152:153], v[118:119], v[148:149], v[22:23]
	global_store_dwordx4 v136, v[150:153], s[16:17] offset:1024 nt
	v_lshlrev_b32_e32 v146, 16, v76
	v_and_b32_e32 v147, 0xffff0000, v76
	v_lshlrev_b32_e32 v148, 16, v77
	v_and_b32_e32 v149, 0xffff0000, v77
	v_pk_mul_f32 v[146:147], v[144:145], v[146:147] op_sel_hi:[0,1]
	v_pk_mul_f32 v[148:149], v[144:145], v[148:149] op_sel_hi:[0,1]
	v_pk_fma_f32 v[150:151], v[120:121], v[146:147], v[24:25]
	v_pk_fma_f32 v[152:153], v[122:123], v[148:149], v[26:27]
	global_store_dwordx4 v136, v[150:153], s[16:17] offset:2048 nt
	v_lshlrev_b32_e32 v146, 16, v78
	v_and_b32_e32 v147, 0xffff0000, v78
	v_lshlrev_b32_e32 v148, 16, v79
	v_and_b32_e32 v149, 0xffff0000, v79
	v_pk_mul_f32 v[146:147], v[144:145], v[146:147] op_sel_hi:[0,1]
	v_pk_mul_f32 v[148:149], v[144:145], v[148:149] op_sel_hi:[0,1]
	v_pk_fma_f32 v[150:151], v[124:125], v[146:147], v[28:29]
	v_pk_fma_f32 v[152:153], v[126:127], v[148:149], v[30:31]
	global_store_dwordx4 v136, v[150:153], s[16:17] offset:3072 nt
	s_cmp_eq_u32 s26, 3
	s_cbranch_scc1 .Lfin_last
	s_lshl_b32 s1, s24, 13
	s_add_u32 s10, s8, s1
	s_addc_u32 s11, s9, 0
	s_add_u32 s12, s10, 0x1000
	s_addc_u32 s13, s11, 0
	s_lshl_b32 s1, s24, 12
	s_add_u32 s18, s54, s1
	s_addc_u32 s19, s55, 0
	s_lshl_b32 s1, s24, 7
	s_add_u32 s20, s74, s1
	s_addc_u32 s21, s75, 0
	v_mov_b32_e32 v128, 0
	s_mov_b32 exec_hi, 0
	global_load_dword v128, v138, s[20:21]
	s_mov_b64 exec, -1
	global_load_dwordx2 v[64:65], v137, s[18:19] offset:0 nt
	global_load_dwordx2 v[66:67], v137, s[18:19] offset:512 nt
	global_load_dwordx2 v[68:69], v137, s[18:19] offset:1024 nt
	global_load_dwordx2 v[70:71], v137, s[18:19] offset:1536 nt
	global_load_dwordx2 v[72:73], v137, s[18:19] offset:2048 nt
	global_load_dwordx2 v[74:75], v137, s[18:19] offset:2560 nt
	global_load_dwordx2 v[76:77], v137, s[18:19] offset:3072 nt
	global_load_dwordx2 v[78:79], v137, s[18:19] offset:3584 nt
	global_load_dwordx4 v[0:3], v136, s[10:11] offset:0 nt
	global_load_dwordx4 v[4:7], v136, s[10:11] offset:1024 nt
	global_load_dwordx4 v[8:11], v136, s[10:11] offset:2048 nt
	global_load_dwordx4 v[12:15], v136, s[10:11] offset:3072 nt
	global_load_dwordx4 v[16:19], v136, s[12:13] offset:0 nt
	global_load_dwordx4 v[20:23], v136, s[12:13] offset:1024 nt
	global_load_dwordx4 v[24:27], v136, s[12:13] offset:2048 nt
	global_load_dwordx4 v[28:31], v136, s[12:13] offset:3072 nt
	s_add_u32 s24, s24, 0x800
	s_waitcnt vmcnt(17)
	s_branch .Lfin_odd

.Lfin_odd:
	v_mov_b32_e32 v140, v129
	ds_bpermute_b32 v141, v130, v140
	s_waitcnt lgkmcnt(0)
	v_add_f32_e32 v140, v140, v141
	ds_bpermute_b32 v141, v131, v140
	s_waitcnt lgkmcnt(0)
	v_add_f32_e32 v140, v140, v141
	ds_bpermute_b32 v141, v132, v140
	s_waitcnt lgkmcnt(0)
	v_add_f32_e32 v140, v140, v141
	ds_bpermute_b32 v141, v133, v140
	s_waitcnt lgkmcnt(0)
	v_add_f32_e32 v140, v140, v141
	ds_bpermute_b32 v141, v134, v140
	s_waitcnt lgkmcnt(0)
	v_add_f32_e32 v140, v140, v141
	ds_bpermute_b32 v141, v135, v140
	s_waitcnt lgkmcnt(0)
	v_add_f32_e32 v140, v140, v141
	v_fmamk_f32 v140, v140, 0x3a000000, v154
	s_mov_b32 s1, 0x800000
	v_mul_f32_e32 v142, 0x4b800000, v140
	v_cmp_gt_f32_e64 s[2:3], s1, v140
	s_nop 1
	v_cndmask_b32_e64 v140, v140, v142, s[2:3]
	v_rsq_f32_e32 v140, v140
	s_nop 0
	v_mul_f32_e32 v142, 0x45800000, v140
	v_cndmask_b32_e64 v144, v140, v142, s[2:3]
	s_lshl_b32 s1, s25, 13
	s_add_u32 s14, s62, s1
	s_addc_u32 s15, s63, 0
	s_add_u32 s16, s14, 0x1000
	s_addc_u32 s17, s15, 0
	s_add_u32 s25, s25, 0x800
	v_lshlrev_b32_e32 v146, 16, v80
	v_and_b32_e32 v147, 0xffff0000, v80
	v_lshlrev_b32_e32 v148, 16, v81
	v_and_b32_e32 v149, 0xffff0000, v81
	v_pk_mul_f32 v[146:147], v[144:145], v[146:147] op_sel_hi:[0,1]
	v_pk_mul_f32 v[148:149], v[144:145], v[148:149] op_sel_hi:[0,1]
	v_pk_fma_f32 v[150:151], v[96:97], v[146:147], v[32:33]
	v_pk_fma_f32 v[152:153], v[98:99], v[148:149], v[34:35]
	global_store_dwordx4 v136, v[150:153], s[14:15] offset:0 nt
	v_lshlrev_b32_e32 v146, 16, v82
	v_and_b32_e32 v147, 0xffff0000, v82
	v_lshlrev_b32_e32 v148, 16, v83
	v_and_b32_e32 v149, 0xffff0000, v83
	v_pk_mul_f32 v[146:147], v[144:145], v[146:147] op_sel_hi:[0,1]
	v_pk_mul_f32 v[148:149], v[144:145], v[148:149] op_sel_hi:[0,1]
	v_pk_fma_f32 v[150:151], v[100:101], v[146:147], v[36:37]
	v_pk_fma_f32 v[152:153], v[102:103], v[148:149], v[38:39]
	global_store_dwordx4 v136, v[150:153], s[14:15] offset:1024 nt
	v_lshlrev_b32_e32 v146, 16, v84
	v_and_b32_e32 v147, 0xffff0000, v84
	v_lshlrev_b32_e32 v148, 16, v85
	v_and_b32_e32 v149, 0xffff0000, v85
	v_pk_mul_f32 v[146:147], v[144:145], v[146:147] op_sel_hi:[0,1]
	v_pk_mul_f32 v[148:149], v[144:145], v[148:149] op_sel_hi:[0,1]
	v_pk_fma_f32 v[150:151], v[104:105], v[146:147], v[40:41]
	v_pk_fma_f32 v[152:153], v[106:107], v[148:149], v[42:43]
	global_store_dwordx4 v136, v[150:153], s[14:15] offset:2048 nt
	v_lshlrev_b32_e32 v146, 16, v86
	v_and_b32_e32 v147, 0xffff0000, v86
	v_lshlrev_b32_e32 v148, 16, v87
	v_and_b32_e32 v149, 0xffff0000, v87
	v_pk_mul_f32 v[146:147], v[144:145], v[146:147] op_sel_hi:[0,1]
	v_pk_mul_f32 v[148:149], v[144:145], v[148:149] op_sel_hi:[0,1]
	v_pk_fma_f32 v[150:151], v[108:109], v[146:147], v[44:45]
	v_pk_fma_f32 v[152:153], v[110:111], v[148:149], v[46:47]
	global_store_dwordx4 v136, v[150:153], s[14:15] offset:3072 nt
	v_lshlrev_b32_e32 v146, 16, v88
	v_and_b32_e32 v147, 0xffff0000, v88
	v_lshlrev_b32_e32 v148, 16, v89
	v_and_b32_e32 v149, 0xffff0000, v89
	v_pk_mul_f32 v[146:147], v[144:145], v[146:147] op_sel_hi:[0,1]
	v_pk_mul_f32 v[148:149], v[144:145], v[148:149] op_sel_hi:[0,1]
	v_pk_fma_f32 v[150:151], v[112:113], v[146:147], v[48:49]
	v_pk_fma_f32 v[152:153], v[114:115], v[148:149], v[50:51]
	global_store_dwordx4 v136, v[150:153], s[16:17] offset:0 nt
	v_lshlrev_b32_e32 v146, 16, v90
	v_and_b32_e32 v147, 0xffff0000, v90
	v_lshlrev_b32_e32 v148, 16, v91
	v_and_b32_e32 v149, 0xffff0000, v91
	v_pk_mul_f32 v[146:147], v[144:145], v[146:147] op_sel_hi:[0,1]
	v_pk_mul_f32 v[148:149], v[144:145], v[148:149] op_sel_hi:[0,1]
	v_pk_fma_f32 v[150:151], v[116:117], v[146:147], v[52:53]
	v_pk_fma_f32 v[152:153], v[118:119], v[148:149], v[54:55]
	global_store_dwordx4 v136, v[150:153], s[16:17] offset:1024 nt
	v_lshlrev_b32_e32 v146, 16, v92
	v_and_b32_e32 v147, 0xffff0000, v92
	v_lshlrev_b32_e32 v148, 16, v93
	v_and_b32_e32 v149, 0xffff0000, v93
	v_pk_mul_f32 v[146:147], v[144:145], v[146:147] op_sel_hi:[0,1]
	v_pk_mul_f32 v[148:149], v[144:145], v[148:149] op_sel_hi:[0,1]
	v_pk_fma_f32 v[150:151], v[120:121], v[146:147], v[56:57]
	v_pk_fma_f32 v[152:153], v[122:123], v[148:149], v[58:59]
	global_store_dwordx4 v136, v[150:153], s[16:17] offset:2048 nt
	v_lshlrev_b32_e32 v146, 16, v94
	v_and_b32_e32 v147, 0xffff0000, v94
	v_lshlrev_b32_e32 v148, 16, v95
	v_and_b32_e32 v149, 0xffff0000, v95
	v_pk_mul_f32 v[146:147], v[144:145], v[146:147] op_sel_hi:[0,1]
	v_pk_mul_f32 v[148:149], v[144:145], v[148:149] op_sel_hi:[0,1]
	v_pk_fma_f32 v[150:151], v[124:125], v[146:147], v[60:61]
	v_pk_fma_f32 v[152:153], v[126:127], v[148:149], v[62:63]
	global_store_dwordx4 v136, v[150:153], s[16:17] offset:3072 nt
	s_add_u32 s26, s26, 1
	s_cmp_lt_u32 s26, 4
	s_cbranch_scc1 .Lfin_loop
